# attention: softmax row sums accumulated on the VALU in f32 (no ones-MFMA in the tile loop)
# baseline (speedup 1.0000x reference)
.LBB0_173:
	s_or_b64 exec, exec, s[6:7]
	s_add_i32 s6, s34, 1
	s_waitcnt vmcnt(1)
	v_add_u32_e32 v24, 0, v116
	s_add_u32 s34, s21, s35
	v_mov_b32_e32 v26, v157
	v_mov_b32_e32 v27, v157
	s_waitcnt vmcnt(0)
	ds_write_b128 v24, v[28:31] offset:13312
	s_addc_u32 s35, s10, 0
	v_mov_b32_e32 v24, v157
	v_mov_b32_e32 v25, v157
	v_mov_b64_e32 v[30:31], v[26:27]
	v_mov_b64_e32 v[34:35], v[26:27]
	v_mov_b64_e32 v[38:39], v[26:27]
	v_mov_b64_e32 v[42:43], v[26:27]
	v_mov_b64_e32 v[46:47], v[26:27]
	v_mov_b64_e32 v[50:51], v[26:27]
	v_mov_b64_e32 v[54:55], v[26:27]
	v_mov_b64_e32 v[58:59], v[26:27]
	v_mov_b64_e32 v[62:63], v[26:27]
	v_lshl_add_u64 v[132:133], v[120:121], 0, s[34:35]
	v_lshl_add_u64 v[134:135], v[122:123], 0, s[2:3]
	v_lshl_add_u64 v[136:137], v[124:125], 0, s[2:3]
	s_mov_b32 s7, 0
	v_mov_b32_e32 v128, 0xf149f2ca
	v_mov_b64_e32 v[28:29], v[24:25]
	v_mov_b64_e32 v[32:33], v[24:25]
	v_mov_b64_e32 v[36:37], v[24:25]
	v_mov_b64_e32 v[40:41], v[24:25]
	v_mov_b64_e32 v[44:45], v[24:25]
	v_mov_b64_e32 v[48:49], v[24:25]
	v_mov_b64_e32 v[52:53], v[24:25]
	v_mov_b64_e32 v[56:57], v[24:25]
	v_mov_b64_e32 v[60:61], v[24:25]
	v_mov_b32_e32 v130, 0xf149f2ca
	s_waitcnt lgkmcnt(0)
	s_barrier
	v_mov_b32_e32 v206, 0
	v_mov_b32_e32 v207, 0
	v_mov_b32_e32 v250, s52
	v_mov_b32_e32 v251, s52
	v_mov_b32_e32 v252, s52
	v_mov_b32_e32 v253, s52
	v_readfirstlane_b32 s2, v160
	s_cmpk_ge_u32 s2, 0x100
	s_cbranch_scc0 .Lattn_noprio
	s_setprio 1

.Lattn_sm:
	v_exp_f32_e32 v92, v92
	v_exp_f32_e32 v93, v93
	v_exp_f32_e32 v94, v94
	v_exp_f32_e32 v95, v95
	v_exp_f32_e32 v96, v96
	v_exp_f32_e32 v97, v97
	v_exp_f32_e32 v98, v98
	v_exp_f32_e32 v99, v99
	v_exp_f32_e32 v100, v100
	v_exp_f32_e32 v101, v101
	v_exp_f32_e32 v102, v102
	v_exp_f32_e32 v103, v103
	v_exp_f32_e32 v104, v104
	v_exp_f32_e32 v105, v105
	v_exp_f32_e32 v106, v106
	v_exp_f32_e32 v107, v107
	v_add_f32_e32 v208, v92, v93
	v_add_f32_e32 v209, v94, v95
	v_add_f32_e32 v208, v208, v96
	v_add_f32_e32 v209, v209, v97
	v_add_f32_e32 v208, v208, v98
	v_add_f32_e32 v209, v209, v99
	v_add_f32_e32 v208, v208, v100
	v_add_f32_e32 v209, v209, v101
	v_add_f32_e32 v208, v208, v102
	v_add_f32_e32 v209, v209, v103
	v_add_f32_e32 v208, v208, v104
	v_add_f32_e32 v209, v209, v105
	v_add_f32_e32 v208, v208, v106
	v_add_f32_e32 v209, v209, v107
	v_add_f32_e32 v208, v208, v209
	v_add_f32_e32 v206, v206, v208
	v_cvt_pk_bf16_f32 v92, v92, v93
	v_cvt_pk_bf16_f32 v93, v94, v95
	v_cvt_pk_bf16_f32 v94, v96, v97
	v_cvt_pk_bf16_f32 v95, v98, v99
	v_cvt_pk_bf16_f32 v96, v100, v101
	v_cvt_pk_bf16_f32 v97, v102, v103
	v_cvt_pk_bf16_f32 v98, v104, v105
	v_cvt_pk_bf16_f32 v99, v106, v107
	v_exp_f32_e32 v76, v76
	v_exp_f32_e32 v77, v77
	v_exp_f32_e32 v78, v78
	v_exp_f32_e32 v79, v79
	v_exp_f32_e32 v80, v80
	v_exp_f32_e32 v81, v81
	v_exp_f32_e32 v82, v82
	v_exp_f32_e32 v83, v83
	v_exp_f32_e32 v84, v84
	v_exp_f32_e32 v85, v85
	v_exp_f32_e32 v86, v86
	v_exp_f32_e32 v87, v87
	v_exp_f32_e32 v88, v88
	v_exp_f32_e32 v89, v89
	v_exp_f32_e32 v90, v90
	v_exp_f32_e32 v91, v91
	v_add_f32_e32 v208, v76, v77
	v_add_f32_e32 v209, v78, v79
	v_add_f32_e32 v208, v208, v80
	v_add_f32_e32 v209, v209, v81
	v_add_f32_e32 v208, v208, v82
	v_add_f32_e32 v209, v209, v83
	v_add_f32_e32 v208, v208, v84
	v_add_f32_e32 v209, v209, v85
	v_add_f32_e32 v208, v208, v86
	v_add_f32_e32 v209, v209, v87
	v_add_f32_e32 v208, v208, v88
	v_add_f32_e32 v209, v209, v89
	v_add_f32_e32 v208, v208, v90
	v_add_f32_e32 v209, v209, v91
	v_add_f32_e32 v208, v208, v209
	v_add_f32_e32 v207, v207, v208
	v_cvt_pk_bf16_f32 v76, v76, v77
	v_cvt_pk_bf16_f32 v77, v78, v79
	v_cvt_pk_bf16_f32 v78, v80, v81
	v_cvt_pk_bf16_f32 v79, v82, v83
	v_cvt_pk_bf16_f32 v80, v84, v85
	v_cvt_pk_bf16_f32 v81, v86, v87
	v_cvt_pk_bf16_f32 v82, v88, v89
	v_cvt_pk_bf16_f32 v83, v90, v91
	s_add_i32 s7, s7, 1
	s_bitcmp1_b32 s7, 0
	s_cselect_b32 s2, 0x5800, 0
	s_add_i32 s10, s2, 0
	v_add_u32_e32 v127, s10, v139
	v_add_u32_e32 v129, s10, v140
	v_add_u32_e32 v131, s10, v116
	s_waitcnt vmcnt(2)
	ds_write_b128 v127, v[72:75]
	s_waitcnt vmcnt(0)
	ds_write_b128 v131, v[64:67] offset:13312
	s_and_b64 vcc, exec, s[42:43]
	s_cbranch_vccz .Lattn_skipw
	ds_write_b128 v129, v[68:71]
.Lattn_skipw:
	s_waitcnt lgkmcnt(15)
	v_mfma_f32_16x16x32_bf16 v[60:63], v[234:237], v[92:95], v[60:63]
	v_mfma_f32_16x16x32_bf16 v[56:59], v[234:237], v[76:79], v[56:59]
	s_waitcnt lgkmcnt(14)
	v_mfma_f32_16x16x32_bf16 v[60:63], v[238:241], v[96:99], v[60:63]
	v_mfma_f32_16x16x32_bf16 v[56:59], v[238:241], v[80:83], v[56:59]
	s_waitcnt lgkmcnt(12)
	v_mfma_f32_16x16x32_bf16 v[52:55], v[242:245], v[92:95], v[52:55]
	v_mfma_f32_16x16x32_bf16 v[48:51], v[242:245], v[76:79], v[48:51]
	s_waitcnt lgkmcnt(10)
	v_mfma_f32_16x16x32_bf16 v[52:55], v[246:249], v[96:99], v[52:55]
	v_mfma_f32_16x16x32_bf16 v[48:51], v[246:249], v[80:83], v[48:51]
	s_waitcnt lgkmcnt(8)
	v_mfma_f32_16x16x32_bf16 v[44:47], v[162:165], v[92:95], v[44:47]
	v_mfma_f32_16x16x32_bf16 v[40:43], v[162:165], v[76:79], v[40:43]
	s_waitcnt lgkmcnt(6)
	v_mfma_f32_16x16x32_bf16 v[44:47], v[166:169], v[96:99], v[44:47]
	v_mfma_f32_16x16x32_bf16 v[40:43], v[166:169], v[80:83], v[40:43]
	s_waitcnt lgkmcnt(4)
	v_mfma_f32_16x16x32_bf16 v[36:39], v[170:173], v[92:95], v[36:39]
	v_mfma_f32_16x16x32_bf16 v[32:35], v[170:173], v[76:79], v[32:35]
	s_waitcnt lgkmcnt(2)
	v_mfma_f32_16x16x32_bf16 v[36:39], v[174:177], v[96:99], v[36:39]
	v_mfma_f32_16x16x32_bf16 v[32:35], v[174:177], v[80:83], v[32:35]
	s_waitcnt lgkmcnt(0)
	s_barrier
	v_lshl_add_u64 v[132:133], v[132:133], 0, s[50:51]
	v_lshl_add_u64 v[134:135], v[134:135], 0, s[4:5]
	v_lshl_add_u64 v[136:137], v[136:137], 0, s[4:5]
	s_cmp_eq_u32 s6, s7
	s_cbranch_scc0 .LBB0_175
	v_mov_b32_e32 v208, v206
	s_nop 1
	v_permlane16_swap_b32_e32 v206, v208
	v_add_f32_e32 v206, v206, v208
	v_mov_b32_e32 v208, v206
	s_nop 1
	v_permlane32_swap_b32_e32 v206, v208
	v_add_f32_e32 v206, v206, v208
	v_mov_b32_e32 v28, v206
	v_mov_b32_e32 v29, v206
	v_mov_b32_e32 v30, v206
	v_mov_b32_e32 v31, v206
	v_mov_b32_e32 v208, v207
	s_nop 1
	v_permlane16_swap_b32_e32 v207, v208
	v_add_f32_e32 v207, v207, v208
	v_mov_b32_e32 v208, v207
	s_nop 1
	v_permlane32_swap_b32_e32 v207, v208
	v_add_f32_e32 v207, v207, v208
	v_mov_b32_e32 v24, v207
	v_mov_b32_e32 v25, v207
	v_mov_b32_e32 v26, v207
	v_mov_b32_e32 v27, v207
	s_branch .LBB0_161
.Lattn_refresh:
	s_waitcnt lgkmcnt(11)
	v_mfma_f32_16x16x32_bf16 v[92:95], v[162:165], v[0:3], 0
	v_mfma_f32_16x16x32_bf16 v[76:79], v[162:165], v[8:11], 0
	ds_read_b64 v[234:235], v147 offset:13312
	ds_read_b64 v[236:237], v147 offset:13344
	s_waitcnt lgkmcnt(12)
	v_mfma_f32_16x16x32_bf16 v[92:95], v[166:169], v[4:7], v[92:95]
	v_mfma_f32_16x16x32_bf16 v[76:79], v[166:169], v[12:15], v[76:79]
	ds_read_b64 v[238:239], v147 offset:13376
	ds_read_b64 v[240:241], v147 offset:13408
	s_waitcnt lgkmcnt(13)
	v_mfma_f32_16x16x32_bf16 v[92:95], v[170:173], v[16:19], v[92:95]
	v_mfma_f32_16x16x32_bf16 v[76:79], v[170:173], v[20:23], v[76:79]
	ds_read_b64 v[242:243], v147 offset:15616
	ds_read_b64 v[244:245], v147 offset:15648
	s_waitcnt lgkmcnt(14)
	v_mfma_f32_16x16x32_bf16 v[96:99], v[174:177], v[0:3], 0
	v_mfma_f32_16x16x32_bf16 v[80:83], v[174:177], v[8:11], 0
	ds_read_b64 v[246:247], v147 offset:15680
	s_waitcnt lgkmcnt(14)
	v_mfma_f32_16x16x32_bf16 v[96:99], v[178:181], v[4:7], v[96:99]
	v_mfma_f32_16x16x32_bf16 v[80:83], v[178:181], v[12:15], v[80:83]
	ds_read_b64 v[248:249], v147 offset:15712
	s_waitcnt lgkmcnt(14)
	v_mfma_f32_16x16x32_bf16 v[96:99], v[182:185], v[16:19], v[96:99]
	v_mfma_f32_16x16x32_bf16 v[80:83], v[182:185], v[20:23], v[80:83]
	ds_read_b64 v[162:163], v147 offset:17920
	s_waitcnt lgkmcnt(14)
	v_mfma_f32_16x16x32_bf16 v[100:103], v[186:189], v[0:3], 0
	v_mfma_f32_16x16x32_bf16 v[84:87], v[186:189], v[8:11], 0
	ds_read_b64 v[164:165], v147 offset:17952
	s_waitcnt lgkmcnt(14)
	v_mfma_f32_16x16x32_bf16 v[100:103], v[214:217], v[4:7], v[100:103]
	v_mfma_f32_16x16x32_bf16 v[84:87], v[214:217], v[12:15], v[84:87]
	ds_read_b64 v[166:167], v147 offset:17984
	s_waitcnt lgkmcnt(14)
	v_mfma_f32_16x16x32_bf16 v[100:103], v[218:221], v[16:19], v[100:103]
	v_mfma_f32_16x16x32_bf16 v[84:87], v[218:221], v[20:23], v[84:87]
	ds_read_b64 v[168:169], v147 offset:18016
	s_waitcnt lgkmcnt(14)
	v_mfma_f32_16x16x32_bf16 v[104:107], v[222:225], v[0:3], 0
	v_mfma_f32_16x16x32_bf16 v[88:91], v[222:225], v[8:11], 0
	ds_read_b64 v[170:171], v147 offset:20224
	s_waitcnt lgkmcnt(14)
	v_mfma_f32_16x16x32_bf16 v[104:107], v[226:229], v[4:7], v[104:107]
	v_mfma_f32_16x16x32_bf16 v[88:91], v[226:229], v[12:15], v[88:91]
	ds_read_b64 v[172:173], v147 offset:20256
	s_waitcnt lgkmcnt(14)
	v_mfma_f32_16x16x32_bf16 v[104:107], v[230:233], v[16:19], v[104:107]
	v_mfma_f32_16x16x32_bf16 v[88:91], v[230:233], v[20:23], v[88:91]
	s_waitcnt lgkmcnt(13)
	ds_read_b64 v[174:175], v147 offset:20288
	ds_read_b64 v[176:177], v147 offset:20320
	s_nop 7
	v_max_f32_e32 v127, v93, v93
	v_max_f32_e32 v129, v92, v92
	v_max_f32_e32 v127, v129, v127
	v_max_f32_e32 v129, v95, v95
	v_max_f32_e32 v131, v94, v94
	v_max_f32_e32 v129, v131, v129
	v_max_f32_e32 v131, v99, v99
	v_max_f32_e32 v147, v98, v98
	v_max_f32_e32 v131, v147, v131
	v_max3_f32 v131, v96, v97, v131
	v_max3_f32 v127, v127, v129, v131
	v_max_f32_e32 v129, v103, v103
	v_max_f32_e32 v131, v102, v102
	v_max_f32_e32 v129, v131, v129
	v_max_f32_e32 v131, v107, v107
	v_max_f32_e32 v147, v106, v106
	v_max_f32_e32 v131, v147, v131
	v_max3_f32 v129, v100, v101, v129
	v_max3_f32 v131, v104, v105, v131
	v_max3_f32 v127, v127, v129, v131
	ds_bpermute_b32 v129, v145, v127
	s_waitcnt lgkmcnt(0)
	v_max_f32_e32 v129, v129, v129
	v_max_f32_e32 v127, v127, v129
	ds_bpermute_b32 v129, v144, v127
	s_waitcnt lgkmcnt(0)
	v_max3_f32 v127, v130, v127, v129
	v_sub_f32_e32 v129, v130, v127
	v_exp_f32_e32 v130, v129
	s_nop 0
	v_pk_mul_f32 v[62:63], v[62:63], v[130:131] op_sel_hi:[1,0]
	v_pk_mul_f32 v[60:61], v[60:61], v[130:131] op_sel_hi:[1,0]
	v_pk_mul_f32 v[54:55], v[54:55], v[130:131] op_sel_hi:[1,0]
	v_pk_mul_f32 v[52:53], v[52:53], v[130:131] op_sel_hi:[1,0]
	v_pk_mul_f32 v[46:47], v[46:47], v[130:131] op_sel_hi:[1,0]
	v_pk_mul_f32 v[44:45], v[44:45], v[130:131] op_sel_hi:[1,0]
	v_pk_mul_f32 v[38:39], v[38:39], v[130:131] op_sel_hi:[1,0]
	v_pk_mul_f32 v[36:37], v[36:37], v[130:131] op_sel_hi:[1,0]
	v_pk_mul_f32 v[30:31], v[30:31], v[130:131] op_sel_hi:[1,0]
	v_pk_mul_f32 v[28:29], v[28:29], v[130:131] op_sel_hi:[1,0]
	v_mul_f32_e32 v206, v206, v130
	v_mov_b32_e32 v130, v127
	v_xor_b32_e32 v148, 0x80000000, v127
	v_xor_b32_e32 v149, 0x80000000, v127
	v_xor_b32_e32 v150, 0x80000000, v127
	v_xor_b32_e32 v151, 0x80000000, v127
	v_max_f32_e32 v127, v77, v77
	v_max_f32_e32 v129, v76, v76
	v_max_f32_e32 v127, v129, v127
	v_max_f32_e32 v129, v79, v79
	v_max_f32_e32 v131, v78, v78
	v_max_f32_e32 v129, v131, v129
	v_max_f32_e32 v131, v83, v83
	v_max_f32_e32 v147, v82, v82
	v_max_f32_e32 v131, v147, v131
	v_max3_f32 v131, v80, v81, v131
	v_max3_f32 v127, v127, v129, v131
	v_max_f32_e32 v129, v87, v87
	v_max_f32_e32 v131, v86, v86
	v_max_f32_e32 v129, v131, v129
	v_max_f32_e32 v131, v91, v91
	v_max_f32_e32 v147, v90, v90
	v_max_f32_e32 v131, v147, v131
	v_max3_f32 v129, v84, v85, v129
	v_max3_f32 v131, v88, v89, v131
	v_max3_f32 v127, v127, v129, v131
	ds_bpermute_b32 v129, v145, v127
	s_waitcnt lgkmcnt(0)
	v_max_f32_e32 v129, v129, v129
	v_max_f32_e32 v127, v127, v129
	ds_bpermute_b32 v129, v144, v127
	s_waitcnt lgkmcnt(0)
	v_max3_f32 v131, v128, v127, v129
	v_sub_f32_e32 v127, v128, v131
	v_exp_f32_e32 v128, v127
	s_nop 0
	v_pk_mul_f32 v[58:59], v[58:59], v[128:129] op_sel_hi:[1,0]
	v_pk_mul_f32 v[56:57], v[56:57], v[128:129] op_sel_hi:[1,0]
	v_pk_mul_f32 v[50:51], v[50:51], v[128:129] op_sel_hi:[1,0]
	v_pk_mul_f32 v[48:49], v[48:49], v[128:129] op_sel_hi:[1,0]
	v_pk_mul_f32 v[42:43], v[42:43], v[128:129] op_sel_hi:[1,0]
	v_pk_mul_f32 v[40:41], v[40:41], v[128:129] op_sel_hi:[1,0]
	v_pk_mul_f32 v[34:35], v[34:35], v[128:129] op_sel_hi:[1,0]
	v_pk_mul_f32 v[32:33], v[32:33], v[128:129] op_sel_hi:[1,0]
	v_pk_mul_f32 v[26:27], v[26:27], v[128:129] op_sel_hi:[1,0]
	v_pk_mul_f32 v[24:25], v[24:25], v[128:129] op_sel_hi:[1,0]
	v_mul_f32_e32 v207, v207, v128
	v_mov_b32_e32 v128, v131
	v_xor_b32_e32 v152, 0x80000000, v131
	v_xor_b32_e32 v153, 0x80000000, v131
	v_xor_b32_e32 v154, 0x80000000, v131
	v_xor_b32_e32 v155, 0x80000000, v131
	v_pk_add_f32 v[92:93], v[92:93], v[130:131] op_sel_hi:[1,0] neg_lo:[0,1] neg_hi:[0,1]
	v_pk_add_f32 v[94:95], v[94:95], v[130:131] op_sel_hi:[1,0] neg_lo:[0,1] neg_hi:[0,1]
	v_pk_add_f32 v[96:97], v[96:97], v[130:131] op_sel_hi:[1,0] neg_lo:[0,1] neg_hi:[0,1]
	v_pk_add_f32 v[98:99], v[98:99], v[130:131] op_sel_hi:[1,0] neg_lo:[0,1] neg_hi:[0,1]
	v_pk_add_f32 v[100:101], v[100:101], v[130:131] op_sel_hi:[1,0] neg_lo:[0,1] neg_hi:[0,1]
	v_pk_add_f32 v[102:103], v[102:103], v[130:131] op_sel_hi:[1,0] neg_lo:[0,1] neg_hi:[0,1]
	v_pk_add_f32 v[104:105], v[104:105], v[130:131] op_sel_hi:[1,0] neg_lo:[0,1] neg_hi:[0,1]
	v_pk_add_f32 v[106:107], v[106:107], v[130:131] op_sel_hi:[1,0] neg_lo:[0,1] neg_hi:[0,1]
	v_pk_add_f32 v[76:77], v[76:77], v[128:129] op_sel_hi:[1,0] neg_lo:[0,1] neg_hi:[0,1]
	v_pk_add_f32 v[78:79], v[78:79], v[128:129] op_sel_hi:[1,0] neg_lo:[0,1] neg_hi:[0,1]
	v_pk_add_f32 v[80:81], v[80:81], v[128:129] op_sel_hi:[1,0] neg_lo:[0,1] neg_hi:[0,1]
	v_pk_add_f32 v[82:83], v[82:83], v[128:129] op_sel_hi:[1,0] neg_lo:[0,1] neg_hi:[0,1]
	v_pk_add_f32 v[84:85], v[84:85], v[128:129] op_sel_hi:[1,0] neg_lo:[0,1] neg_hi:[0,1]
	v_pk_add_f32 v[86:87], v[86:87], v[128:129] op_sel_hi:[1,0] neg_lo:[0,1] neg_hi:[0,1]
	v_pk_add_f32 v[88:89], v[88:89], v[128:129] op_sel_hi:[1,0] neg_lo:[0,1] neg_hi:[0,1]
	v_pk_add_f32 v[90:91], v[90:91], v[128:129] op_sel_hi:[1,0] neg_lo:[0,1] neg_hi:[0,1]
	s_branch .Lattn_sm
